# prep phase stores (H, transposed weights, gates, rope) write-through (sc1): no dirty L2 left for the first grid barrier's write-back
# baseline (speedup 1.0000x reference)
; __device__ __forceinline__ void p0_prep(const Params& p, LAS unsigned char* lds) {
;     ...
;     for (int tI = bid; tI < 928; tI += G) {
;         const float* src; bf16_t* dst; int ldn, Kdim, ns, kt, srccol;
;         int u = tI;
;         if (u < 768) { ns = u >> 4; kt = u & 15; src = p.w_in; ldn = INW; Kdim = 1024; dst = (bf16_t*)(ws + WS_WIN); srccol = ns * 256 + (ns >= 20 ? 8 : 0); }
;         else if (u < 832) { u -= 768; ns = u >> 4; kt = u & 15; src = p.w_pm; ldn = 1024; Kdim = 1024; dst = (bf16_t*)(ws + WS_WPM); srccol = ns * 256; }
;         else if (u < 864) { u -= 832; ns = u >> 3; kt = u & 7; src = p.w_pa; ldn = 1024; Kdim = 512; dst = (bf16_t*)(ws + WS_WPA); srccol = ns * 256; }
;         else { u -= 864; ns = u >> 4; kt = u & 15; src = p.w_out; ldn = 1024; Kdim = 1024; dst = (bf16_t*)(ws + WS_WOUT); srccol = ns * 256; }
;         float4 v[8];
; #pragma unroll
;         for (int i = 0; i < 8; ++i) { const int idx = tid + 512 * i; const int k = idx >> 6, n4 = idx & 63; const f32x4 t = __builtin_nontemporal_load((const f32x4*)(src + (size_t)(kt * 64 + k) * ldn + srccol + 4 * n4)); v[i] = make_float4(t[0], t[1], t[2], t[3]); }
; #pragma unroll
;         for (int i = 0; i < 8; ++i) { const int idx = tid + 512 * i; const int k = idx >> 6, n4 = idx & 63;
;             strip[k * 257 + 4 * n4 + 0] = v[i].x; strip[k * 257 + 4 * n4 + 1] = v[i].y; strip[k * 257 + 4 * n4 + 2] = v[i].z; strip[k * 257 + 4 * n4 + 3] = v[i].w; }
;         __syncthreads();
; #pragma unroll
;         for (int j = 0; j < 4; ++j) { const int piece = tid + 512 * j; const int n = piece >> 3, kv = piece & 7; float f[8];
; #pragma unroll
;             for (int e = 0; e < 8; ++e) f[e] = strip[(kv * 8 + e) * 257 + n];
;             *(u32x4*)(dst + (size_t)(ns * 256 + n) * Kdim + kt * 64 + kv * 8) = pack8(f); }
;         __syncthreads();
.LBB0_25:
	s_ashr_i32 s19, s18, 31
	s_lshl_b32 s17, s25, 6
	s_lshl_b64 s[18:19], s[18:19], 2
	s_add_u32 s14, s14, s18
	s_addc_u32 s15, s15, s19
	v_or_b32_e32 v30, s17, v6
	v_or_b32_e32 v32, s17, v7
	v_or_b32_e32 v38, s17, v8
	v_or_b32_e32 v40, s17, v9
	v_or_b32_e32 v46, s17, v10
	v_or_b32_e32 v48, s17, v11
	v_lshl_add_u64 v[58:59], s[14:15], 0, v[0:1]
	v_mul_hi_u32_u24_e32 v31, s16, v30
	v_mul_u32_u24_e32 v30, s16, v30
	v_mul_hi_u32_u24_e32 v33, s16, v32
	v_mul_u32_u24_e32 v32, s16, v32
	v_mul_hi_u32_u24_e32 v39, s16, v38
	v_mul_u32_u24_e32 v38, s16, v38
	v_mul_hi_u32_u24_e32 v41, s16, v40
	v_mul_u32_u24_e32 v40, s16, v40
	v_mul_hi_u32_u24_e32 v47, s16, v46
	v_mul_u32_u24_e32 v46, s16, v46
	v_mul_hi_u32_u24_e32 v49, s16, v48
	v_mul_u32_u24_e32 v48, s16, v48
	v_lshl_add_u64 v[30:31], v[30:31], 2, v[58:59]
	v_lshl_add_u64 v[34:35], v[32:33], 2, v[58:59]
	v_lshl_add_u64 v[38:39], v[38:39], 2, v[58:59]
	v_lshl_add_u64 v[42:43], v[40:41], 2, v[58:59]
	v_lshl_add_u64 v[46:47], v[46:47], 2, v[58:59]
	v_lshl_add_u64 v[50:51], v[48:49], 2, v[58:59]
	global_load_dwordx4 v[30:33], v[30:31], off nt
	s_nop 0
	global_load_dwordx4 v[34:37], v[34:35], off nt
	s_nop 0
	global_load_dwordx4 v[38:41], v[38:39], off nt
	s_nop 0
	global_load_dwordx4 v[42:45], v[42:43], off nt
	s_nop 0
	global_load_dwordx4 v[46:49], v[46:47], off nt
	s_nop 0
	global_load_dwordx4 v[50:53], v[50:51], off nt
	v_or_b32_e32 v54, s17, v12
	v_mul_hi_u32_u24_e32 v55, s16, v54
	v_mul_u32_u24_e32 v54, s16, v54
	v_lshl_add_u64 v[54:55], v[54:55], 2, v[58:59]
	v_add_u32_e32 v60, s17, v13
	global_load_dwordx4 v[54:57], v[54:55], off nt
	v_mul_hi_u32_u24_e32 v61, s16, v60
	v_mul_u32_u24_e32 v60, s16, v60
	v_lshl_add_u64 v[58:59], v[60:61], 2, v[58:59]
	global_load_dwordx4 v[58:61], v[58:59], off nt
	v_add_u32_e32 v62, s24, v4
	v_ashrrev_i32_e32 v64, 31, v62
	v_mul_lo_u32 v65, s7, v62
	v_mad_u64_u32 v[62:63], s[14:15], s6, v62, 0
	s_lshl_b32 s14, s25, 7
	s_add_u32 s8, s8, s14
	v_mul_lo_u32 v64, s6, v64
	s_addc_u32 s9, s9, 0
	v_add3_u32 v63, v63, v64, v65
	v_lshl_add_u64 v[64:65], s[8:9], 0, v[2:3]
	s_add_i32 s23, s23, s82
	s_add_i32 s22, s22, s12
	s_add_i32 s20, s20, s21
	s_cmpk_gt_i32 s23, 0x39f
	s_waitcnt vmcnt(7)
	ds_write2_b32 v16, v30, v31 offset1:1
	ds_write2_b32 v16, v32, v33 offset0:2 offset1:3
	s_waitcnt vmcnt(6)
	ds_write2_b32 v17, v34, v35 offset1:1
	ds_write2_b32 v17, v36, v37 offset0:2 offset1:3
	s_waitcnt vmcnt(5)
	ds_write2_b32 v18, v38, v39 offset1:1
	ds_write2_b32 v18, v40, v41 offset0:2 offset1:3
	s_waitcnt vmcnt(4)
	ds_write2_b32 v19, v42, v43 offset1:1
	ds_write2_b32 v19, v44, v45 offset0:2 offset1:3
	s_waitcnt vmcnt(3)
	ds_write2_b32 v20, v46, v47 offset1:1
	ds_write2_b32 v21, v48, v49 offset1:1
	s_waitcnt vmcnt(2)
	ds_write2_b32 v22, v50, v51 offset1:1
	ds_write2_b32 v22, v52, v53 offset0:2 offset1:3
	s_waitcnt vmcnt(1)
	ds_write2_b32 v23, v54, v55 offset1:1
	ds_write2_b32 v24, v56, v57 offset1:1
	s_waitcnt vmcnt(0)
	ds_write2_b32 v25, v58, v59 offset1:1
	ds_write2_b32 v25, v60, v61 offset0:2 offset1:3
	s_waitcnt lgkmcnt(0)
	s_barrier
	ds_read_b32 v30, v26
	ds_read_b32 v31, v26 offset:1028
	ds_read_b32 v32, v26 offset:2056
	ds_read_b32 v33, v26 offset:3084
	ds_read_b32 v36, v26 offset:4112
	ds_read_b32 v37, v26 offset:5140
	ds_read_b32 v38, v26 offset:6168
	ds_read_b32 v39, v26 offset:7196
	v_lshl_add_u64 v[34:35], v[62:63], 1, v[64:65]
	s_waitcnt lgkmcnt(6)
	v_cvt_pk_bf16_f32 v30, v30, v31
	s_waitcnt lgkmcnt(4)
	v_cvt_pk_bf16_f32 v31, v32, v33
	s_waitcnt lgkmcnt(2)
	v_cvt_pk_bf16_f32 v32, v36, v37
	s_waitcnt lgkmcnt(0)
	v_cvt_pk_bf16_f32 v33, v38, v39
	ds_read_b32 v36, v27
	ds_read_b32 v37, v27 offset:1028
	ds_read_b32 v38, v27 offset:2056
	ds_read_b32 v39, v27 offset:3084
	ds_read_b32 v40, v27 offset:4112
	ds_read_b32 v41, v27 offset:5140
	ds_read_b32 v42, v27 offset:6168
	ds_read_b32 v43, v27 offset:7196
	global_store_dwordx4 v[34:35], v[30:33], off sc1
	v_add_u32_e32 v34, s24, v14
	v_ashrrev_i32_e32 v35, 31, v34
	s_waitcnt lgkmcnt(6)
	v_cvt_pk_bf16_f32 v30, v36, v37
	v_mul_lo_u32 v36, s6, v35
	v_mul_lo_u32 v37, s7, v34
	v_mad_u64_u32 v[34:35], s[8:9], s6, v34, 0
	v_add3_u32 v35, v35, v36, v37
	s_waitcnt lgkmcnt(4)
	v_cvt_pk_bf16_f32 v31, v38, v39
	s_waitcnt lgkmcnt(2)
	v_cvt_pk_bf16_f32 v32, v40, v41
	s_waitcnt lgkmcnt(0)
	v_cvt_pk_bf16_f32 v33, v42, v43
	v_lshl_add_u64 v[34:35], v[34:35], 1, v[64:65]
	ds_read_b32 v36, v28
	ds_read_b32 v37, v28 offset:1028
	ds_read_b32 v38, v28 offset:2056
	ds_read_b32 v39, v28 offset:3084
	ds_read_b32 v40, v28 offset:4112
	ds_read_b32 v41, v28 offset:5140
	ds_read_b32 v42, v28 offset:6168
	ds_read_b32 v43, v28 offset:7196
	global_store_dwordx4 v[34:35], v[30:33], off sc1
	v_add_u32_e32 v34, s24, v15
	v_ashrrev_i32_e32 v35, 31, v34
	s_waitcnt lgkmcnt(6)
	v_cvt_pk_bf16_f32 v30, v36, v37
	v_mul_lo_u32 v36, s6, v35
	v_mul_lo_u32 v37, s7, v34
	v_mad_u64_u32 v[34:35], s[8:9], s6, v34, 0
	v_add3_u32 v35, v35, v36, v37
	s_waitcnt lgkmcnt(4)
	v_cvt_pk_bf16_f32 v31, v38, v39
	s_waitcnt lgkmcnt(2)
	v_cvt_pk_bf16_f32 v32, v40, v41
	s_waitcnt lgkmcnt(0)
	v_cvt_pk_bf16_f32 v33, v42, v43
	v_lshl_add_u64 v[34:35], v[34:35], 1, v[64:65]
	ds_read_b32 v36, v29
	ds_read_b32 v37, v29 offset:1028
	ds_read_b32 v38, v29 offset:2056
	ds_read_b32 v39, v29 offset:3084
	ds_read_b32 v40, v29 offset:4112
	ds_read_b32 v41, v29 offset:5140
	ds_read_b32 v42, v29 offset:6168
	ds_read_b32 v43, v29 offset:7196
	global_store_dwordx4 v[34:35], v[30:33], off sc1
	v_add_u32_e32 v34, s24, v5
	v_ashrrev_i32_e32 v35, 31, v34
	s_waitcnt lgkmcnt(6)
	v_cvt_pk_bf16_f32 v30, v36, v37
	v_mul_lo_u32 v36, s6, v35
	v_mul_lo_u32 v37, s7, v34
	v_mad_u64_u32 v[34:35], s[6:7], s6, v34, 0
	v_add3_u32 v35, v35, v36, v37
	s_waitcnt lgkmcnt(4)
	v_cvt_pk_bf16_f32 v31, v38, v39
	s_waitcnt lgkmcnt(2)
	v_cvt_pk_bf16_f32 v32, v40, v41
	s_waitcnt lgkmcnt(0)
	v_cvt_pk_bf16_f32 v33, v42, v43
	v_lshl_add_u64 v[34:35], v[34:35], 1, v[64:65]
	global_store_dwordx4 v[34:35], v[30:33], off sc1
	s_barrier
	s_cbranch_scc1 .LBB0_37

; __device__ __forceinline__ void p0_prep(const Params& p, LAS unsigned char* lds) {
;     ...
;             if ((lane & 7) == 0) {
;                 const int j = (h32 ? 4 : 0) + (h16 ? 2 : 0) + (h8 ? 1 : 0);
;                 const float gv = gt + bias_l;
;                 GATES[(size_t)row * 8 + j] = (j < 4) ? gv : (fminf(gv, 0.f) - log1pf(expf(-fabsf(gv))));
;             }
.LBB0_39:
	s_or_b64 exec, exec, s[26:27]
	global_store_dword v[164:165], v128, off sc1

; #define LAS __attribute__((address_space(3)))
; __device__ __forceinline__ unsigned cvt_pk_bf16(float lo, float hi) { const f32x2_t f = {lo, hi}; const bf16x2_t b = __builtin_convertvector(f, bf16x2_t); return __builtin_bit_cast(unsigned, b); }
; __device__ __forceinline__ void p0_prep(const Params& p, LAS unsigned char* lds) {
;     ...
;     for (int row0 = (bid * 8 + wid) * 2; row0 < T_TOK; row0 += G * 16) {
;         float4 v[2][4];
; #pragma unroll
;         for (int rr = 0; rr < 2; ++rr)
; #pragma unroll
;             for (int i = 0; i < 4; ++i) { const f32x4 t = __builtin_nontemporal_load((const f32x4*)(p.x + (size_t)(row0 + rr) * 1024) + (i * 64 + lane)); v[rr][i] = make_float4(t[0], t[1], t[2], t[3]); }
; #pragma unroll
;         for (int rr = 0; rr < 2; ++rr) {
;             const int row = row0 + rr;
;             float ss = 0.f;
; #pragma unroll
;             for (int i = 0; i < 4; ++i) ss += v[rr][i].x * v[rr][i].x + v[rr][i].y * v[rr][i].y + v[rr][i].z * v[rr][i].z + v[rr][i].w * v[rr][i].w;
;             ss = wave_sum(ss);
;             const float rstd = rsqrtf(ss * (1.0f / 1024.0f) + EPS);
;             float g[8];
; #pragma unroll
;             for (int j = 0; j < 8; ++j) g[j] = 0.f;
; #pragma unroll
;             for (int i = 0; i < 4; ++i) {
;                 const float4 pw = ((const float4*)p.pre_w)[i * 64 + lane];
;                 float hv[4] = {v[rr][i].x * rstd * pw.x, v[rr][i].y * rstd * pw.y, v[rr][i].z * rstd * pw.z, v[rr][i].w * rstd * pw.w};
;                 u32x2 w; w.x = cvt_pk_bf16(hv[0], hv[1]); w.y = cvt_pk_bf16(hv[2], hv[3]);
;                 *(u32x2*)(H + (size_t)row * 1024 + (i * 64 + lane) * 4) = w;
; #pragma unroll
;                 for (int e = 0; e < 4; ++e) {
;                     const int k = (i * 64 + lane) * 4 + e;
;                     const f32x4 wa = *(const LAS f32x4*)(WG + k * 8), wb = *(const LAS f32x4*)(WG + k * 8 + 4);
;                     g[0] += hv[e] * wa[0]; g[1] += hv[e] * wa[1]; g[2] += hv[e] * wa[2]; g[3] += hv[e] * wa[3];
;                     g[4] += hv[e] * wb[0]; g[5] += hv[e] * wb[1]; g[6] += hv[e] * wb[2]; g[7] += hv[e] * wb[3];
;                 }
;             }
.LBB0_41:
	global_load_dwordx4 v[152:155], v[166:167], off offset:-4096 nt
	global_load_dwordx4 v[148:151], v[166:167], off offset:-3072 nt
	global_load_dwordx4 v[144:147], v[166:167], off offset:-2048 nt
	global_load_dwordx4 v[156:159], v[166:167], off offset:-1024 nt
	global_load_dwordx4 v[182:185], v[162:163], off
	s_waitcnt vmcnt(4)
	v_mov_b32_e32 v130, v153
	s_waitcnt vmcnt(3)
	v_mov_b32_e32 v131, v149
	v_mov_b32_e32 v128, v152
	s_waitcnt lgkmcnt(0)
	v_mov_b32_e32 v129, v148
	s_waitcnt vmcnt(2)
	v_mov_b32_e32 v134, v145
	s_waitcnt vmcnt(1)
	v_mov_b32_e32 v135, v157
	v_pk_mul_f32 v[130:131], v[130:131], v[130:131]
	v_mov_b32_e32 v132, v144
	v_mov_b32_e32 v133, v156
	v_mov_b32_e32 v136, v154
	v_mov_b32_e32 v137, v150
	v_pk_mul_f32 v[134:135], v[134:135], v[134:135]
	v_pk_fma_f32 v[128:129], v[128:129], v[128:129], v[130:131]
	v_mov_b32_e32 v138, v146
	v_mov_b32_e32 v139, v158
	v_mov_b32_e32 v140, v155
	v_mov_b32_e32 v141, v151
	v_pk_fma_f32 v[130:131], v[132:133], v[132:133], v[134:135]
	v_pk_fma_f32 v[128:129], v[136:137], v[136:137], v[128:129]
	v_mov_b32_e32 v142, v147
	v_mov_b32_e32 v143, v159
	v_pk_fma_f32 v[130:131], v[138:139], v[138:139], v[130:131]
	v_pk_fma_f32 v[128:129], v[140:141], v[140:141], v[128:129]
	v_pk_fma_f32 v[130:131], v[142:143], v[142:143], v[130:131]
	v_add_f32_e32 v128, v128, v129
	v_add_f32_e32 v128, v128, v130
	v_add_f32_e32 v128, v128, v131
	ds_bpermute_b32 v129, v173, v128
	s_waitcnt lgkmcnt(0)
	v_add_f32_e32 v128, v128, v129
	ds_bpermute_b32 v129, v174, v128
	s_waitcnt lgkmcnt(0)
	v_add_f32_e32 v128, v128, v129
	ds_bpermute_b32 v129, v175, v128
	s_waitcnt lgkmcnt(0)
	v_add_f32_e32 v128, v128, v129
	ds_bpermute_b32 v129, v176, v128
	s_waitcnt lgkmcnt(0)
	v_add_f32_e32 v128, v128, v129
	ds_bpermute_b32 v129, v177, v128
	s_waitcnt lgkmcnt(0)
	v_add_f32_e32 v128, v128, v129
	ds_bpermute_b32 v129, v178, v128
	s_waitcnt lgkmcnt(0)
	v_add_f32_e32 v128, v128, v129
	v_fmamk_f32 v128, v128, 0x3a800000, v161
	v_mul_f32_e32 v129, 0x4b800000, v128
	v_cmp_gt_f32_e64 s[0:1], s13, v128
	s_nop 1
	v_cndmask_b32_e64 v128, v128, v129, s[0:1]
	v_rsq_f32_e32 v171, v128
	global_load_dwordx4 v[140:143], v[166:167], off nt
	global_load_dwordx4 v[136:139], v[166:167], off offset:1024 nt
	global_load_dwordx4 v[132:135], v[166:167], off offset:2048 nt
	global_load_dwordx4 v[128:131], v[166:167], off offset:3072 nt
	v_mul_f32_e32 v181, 0x45800000, v171
	v_cndmask_b32_e64 v186, v171, v181, s[0:1]
	v_pk_mul_f32 v[152:153], v[152:153], v[186:187] op_sel_hi:[1,0]
	v_pk_mul_f32 v[154:155], v[154:155], v[186:187] op_sel_hi:[1,0]
	s_waitcnt vmcnt(4)
	v_pk_mul_f32 v[182:183], v[182:183], v[152:153]
	v_pk_mul_f32 v[184:185], v[184:185], v[154:155]
	v_cvt_pk_bf16_f32 v152, v182, v183
	v_cvt_pk_bf16_f32 v153, v184, v185
	global_store_dwordx2 v[168:169], v[152:153], off offset:-3584 sc1
	global_load_dwordx4 v[152:155], v[162:163], off offset:1024
	v_pk_mul_f32 v[148:149], v[148:149], v[186:187] op_sel_hi:[1,0]
	v_pk_mul_f32 v[150:151], v[150:151], v[186:187] op_sel_hi:[1,0]
	v_pk_mul_f32 v[144:145], v[144:145], v[186:187] op_sel_hi:[1,0]
	v_pk_mul_f32 v[146:147], v[146:147], v[186:187] op_sel_hi:[1,0]
	v_pk_mul_f32 v[156:157], v[156:157], v[186:187] op_sel_hi:[1,0]
	v_pk_mul_f32 v[158:159], v[158:159], v[186:187] op_sel_hi:[1,0]
	v_fma_f32 v171, v0, v182, 0
	v_fma_f32 v181, v1, v182, 0
	v_fma_f32 v186, v2, v182, 0
	v_fma_f32 v187, v3, v182, 0
	v_fma_f32 v188, v4, v182, 0
	v_fma_f32 v189, v5, v182, 0
	v_fma_f32 v191, v6, v182, 0
	v_fma_f32 v182, v7, v182, 0
	v_fmac_f32_e32 v171, v8, v183
	v_fmac_f32_e32 v181, v9, v183
	v_fmac_f32_e32 v186, v10, v183
	v_fmac_f32_e32 v187, v11, v183
	v_fmac_f32_e32 v188, v12, v183
	v_fmac_f32_e32 v189, v13, v183
	v_fmac_f32_e32 v191, v14, v183
	v_fmac_f32_e32 v182, v15, v183
	v_fmac_f32_e32 v171, v16, v184
	v_fmac_f32_e32 v181, v17, v184
	v_fmac_f32_e32 v186, v18, v184
	v_fmac_f32_e32 v187, v19, v184
	v_fmac_f32_e32 v188, v184, v20
	v_fmac_f32_e32 v189, v184, v21
	v_fmac_f32_e32 v191, v184, v22
	v_fmac_f32_e32 v182, v184, v23
	v_fmac_f32_e32 v171, v185, v24
	v_fmac_f32_e32 v181, v185, v25
	v_fmac_f32_e32 v186, v185, v26
	v_fmac_f32_e32 v187, v185, v27
	v_fmac_f32_e32 v188, v185, v28
	v_fmac_f32_e32 v189, v185, v29
	v_fmac_f32_e32 v191, v185, v30
	v_fmac_f32_e32 v182, v185, v31
	s_waitcnt vmcnt(0)
	v_pk_mul_f32 v[152:153], v[148:149], v[152:153]
	v_pk_mul_f32 v[154:155], v[150:151], v[154:155]
	v_cvt_pk_bf16_f32 v148, v152, v153
	v_cvt_pk_bf16_f32 v149, v154, v155
	global_store_dwordx2 v[168:169], v[148:149], off offset:-3072 sc1
	global_load_dwordx4 v[148:151], v[162:163], off offset:2048
	v_fmac_f32_e32 v171, v152, v32
	v_fmac_f32_e32 v181, v152, v33
	v_fmac_f32_e32 v186, v152, v34
	v_fmac_f32_e32 v187, v152, v35
	v_fmac_f32_e32 v188, v152, v36
	v_fmac_f32_e32 v189, v152, v37
	v_fmac_f32_e32 v191, v152, v38
	v_fmac_f32_e32 v182, v152, v39
	v_fmac_f32_e32 v171, v153, v40
	v_fmac_f32_e32 v181, v153, v41
	v_fmac_f32_e32 v186, v153, v42
	v_fmac_f32_e32 v187, v153, v43
	v_fmac_f32_e32 v188, v153, v44
	v_fmac_f32_e32 v189, v153, v45
	v_fmac_f32_e32 v191, v153, v46
	v_fmac_f32_e32 v182, v153, v47
	v_fmac_f32_e32 v171, v154, v48
	v_fmac_f32_e32 v181, v154, v49
	v_fmac_f32_e32 v186, v154, v50
	v_fmac_f32_e32 v187, v154, v51
	v_fmac_f32_e32 v188, v154, v52
	v_fmac_f32_e32 v189, v154, v53
	v_fmac_f32_e32 v191, v154, v54
	v_fmac_f32_e32 v182, v154, v55
	v_fmac_f32_e32 v171, v155, v56
	v_fmac_f32_e32 v181, v155, v57
	v_fmac_f32_e32 v186, v155, v58
	v_fmac_f32_e32 v187, v155, v59
	v_fmac_f32_e32 v188, v155, v60
	v_fmac_f32_e32 v189, v155, v61
	v_fmac_f32_e32 v191, v155, v62
	v_fmac_f32_e32 v182, v155, v63
	s_waitcnt vmcnt(0)
; #define LAS __attribute__((address_space(3)))
; __device__ __forceinline__ unsigned cvt_pk_bf16(float lo, float hi) { const f32x2_t f = {lo, hi}; const bf16x2_t b = __builtin_convertvector(f, bf16x2_t); return __builtin_bit_cast(unsigned, b); }
; __device__ __forceinline__ void p0_prep(const Params& p, LAS unsigned char* lds) {
;     ...
;             for (int i = 0; i < 4; ++i) {
;                 const float4 pw = ((const float4*)p.pre_w)[i * 64 + lane];
;                 float hv[4] = {v[rr][i].x * rstd * pw.x, v[rr][i].y * rstd * pw.y, v[rr][i].z * rstd * pw.z, v[rr][i].w * rstd * pw.w};
;                 u32x2 w; w.x = cvt_pk_bf16(hv[0], hv[1]); w.y = cvt_pk_bf16(hv[2], hv[3]);
;                 *(u32x2*)(H + (size_t)row * 1024 + (i * 64 + lane) * 4) = w;
; #pragma unroll
;                 for (int e = 0; e < 4; ++e) {
;                     const int k = (i * 64 + lane) * 4 + e;
;                     const f32x4 wa = *(const LAS f32x4*)(WG + k * 8), wb = *(const LAS f32x4*)(WG + k * 8 + 4);
;                     g[0] += hv[e] * wa[0]; g[1] += hv[e] * wa[1]; g[2] += hv[e] * wa[2]; g[3] += hv[e] * wa[3];
;                     g[4] += hv[e] * wb[0]; g[5] += hv[e] * wb[1]; g[6] += hv[e] * wb[2]; g[7] += hv[e] * wb[3];
;                 }
;             }
;             const bool h32 = (lane & 32) != 0, h16 = (lane & 16) != 0, h8 = (lane & 8) != 0;
;             float t4[4], t2[2];
; #pragma unroll
;             for (int j = 0; j < 4; ++j) { const float send = h32 ? g[j] : g[j + 4], keep = h32 ? g[j + 4] : g[j]; t4[j] = keep + __shfl_xor(send, 32); }
; #pragma unroll
;             for (int j = 0; j < 2; ++j) { const float send = h16 ? t4[j] : t4[j + 2], keep = h16 ? t4[j + 2] : t4[j]; t2[j] = keep + __shfl_xor(send, 16); }
;             float gt; { const float send = h8 ? t2[0] : t2[1], keep = h8 ? t2[1] : t2[0]; gt = keep + __shfl_xor(send, 8); }
;             gt += __shfl_xor(gt, 4); gt += __shfl_xor(gt, 2); gt += __shfl_xor(gt, 1);
;             if ((lane & 7) == 0) {
	v_pk_mul_f32 v[148:149], v[144:145], v[148:149]
	v_pk_mul_f32 v[150:151], v[146:147], v[150:151]
	v_cvt_pk_bf16_f32 v144, v148, v149
	v_cvt_pk_bf16_f32 v145, v150, v151
	global_store_dwordx2 v[168:169], v[144:145], off offset:-2560 sc1
	global_load_dwordx4 v[144:147], v[162:163], off offset:3072
	v_fmac_f32_e32 v171, v148, v64
	v_fmac_f32_e32 v181, v148, v65
	v_fmac_f32_e32 v186, v148, v66
	v_fmac_f32_e32 v187, v148, v67
	v_fmac_f32_e32 v188, v148, v68
	v_fmac_f32_e32 v189, v148, v69
	v_fmac_f32_e32 v191, v148, v70
	v_fmac_f32_e32 v182, v148, v71
	v_fmac_f32_e32 v171, v149, v72
	v_fmac_f32_e32 v181, v149, v73
	v_fmac_f32_e32 v186, v149, v74
	v_fmac_f32_e32 v187, v149, v75
	v_fmac_f32_e32 v188, v149, v76
	v_fmac_f32_e32 v189, v149, v77
	v_fmac_f32_e32 v191, v149, v78
	v_fmac_f32_e32 v182, v149, v79
	v_fmac_f32_e32 v171, v150, v80
	v_fmac_f32_e32 v181, v150, v81
	v_fmac_f32_e32 v186, v150, v82
	v_fmac_f32_e32 v187, v150, v83
	v_fmac_f32_e32 v188, v150, v84
	v_fmac_f32_e32 v189, v150, v85
	v_fmac_f32_e32 v191, v150, v86
	v_fmac_f32_e32 v182, v150, v87
	v_fmac_f32_e32 v171, v151, v88
	v_fmac_f32_e32 v181, v151, v89
	v_fmac_f32_e32 v186, v151, v90
	v_fmac_f32_e32 v187, v151, v91
	v_fmac_f32_e32 v188, v151, v92
	v_fmac_f32_e32 v189, v151, v93
	v_fmac_f32_e32 v191, v151, v94
	v_fmac_f32_e32 v182, v151, v95
	s_waitcnt vmcnt(0)
	v_pk_mul_f32 v[148:149], v[156:157], v[144:145]
	s_nop 0
	v_fmac_f32_e32 v171, v148, v96
	v_fmac_f32_e32 v188, v148, v100
	v_fmac_f32_e32 v181, v148, v97
	v_fmac_f32_e32 v189, v148, v101
	v_fmac_f32_e32 v186, v148, v98
	v_fmac_f32_e32 v191, v148, v102
	v_fmac_f32_e32 v187, v148, v99
	v_fmac_f32_e32 v182, v148, v103
	v_pk_mul_f32 v[146:147], v[158:159], v[146:147]
	v_fmac_f32_e32 v171, v149, v104
	v_fmac_f32_e32 v188, v149, v108
	v_fmac_f32_e32 v181, v149, v105
	v_fmac_f32_e32 v189, v149, v109
	v_fmac_f32_e32 v186, v149, v106
	v_fmac_f32_e32 v191, v149, v110
	v_fmac_f32_e32 v187, v149, v107
	v_fmac_f32_e32 v182, v149, v111
	v_fmac_f32_e32 v171, v146, v112
	v_fmac_f32_e32 v188, v146, v116
	v_fmac_f32_e32 v181, v146, v113
	v_fmac_f32_e32 v189, v146, v117
	v_fmac_f32_e32 v186, v146, v114
	v_fmac_f32_e32 v191, v146, v118
	v_fmac_f32_e32 v187, v146, v115
	v_fmac_f32_e32 v182, v146, v119
	v_fmac_f32_e32 v171, v147, v120
	v_fmac_f32_e32 v188, v147, v124
	v_fmac_f32_e32 v181, v147, v121
	v_fmac_f32_e32 v189, v147, v125
	v_fmac_f32_e32 v186, v147, v122
	v_fmac_f32_e32 v191, v147, v126
	v_fmac_f32_e32 v187, v147, v123
	v_fmac_f32_e32 v182, v147, v127
	v_cndmask_b32_e32 v144, v171, v188, vcc
	v_cndmask_b32_e32 v150, v181, v189, vcc
	v_cndmask_b32_e32 v152, v186, v191, vcc
	v_cndmask_b32_e32 v154, v187, v182, vcc
	ds_bpermute_b32 v144, v173, v144
	ds_bpermute_b32 v150, v173, v150
	ds_bpermute_b32 v152, v173, v152
	ds_bpermute_b32 v154, v173, v154
	v_cndmask_b32_e32 v145, v188, v171, vcc
	v_cndmask_b32_e32 v151, v189, v181, vcc
	v_cndmask_b32_e32 v153, v191, v186, vcc
	v_cndmask_b32_e32 v155, v182, v187, vcc
	s_waitcnt lgkmcnt(3)
	v_add_f32_e32 v144, v145, v144
	s_waitcnt lgkmcnt(2)
	v_add_f32_e32 v145, v151, v150
	s_waitcnt lgkmcnt(1)
	v_add_f32_e32 v150, v153, v152
	s_waitcnt lgkmcnt(0)
	v_add_f32_e32 v151, v155, v154
	v_cndmask_b32_e64 v152, v144, v150, s[2:3]
	v_cndmask_b32_e64 v153, v145, v151, s[2:3]
	ds_bpermute_b32 v152, v174, v152
	ds_bpermute_b32 v153, v174, v153
	v_cndmask_b32_e64 v144, v150, v144, s[2:3]
	v_cndmask_b32_e64 v145, v151, v145, s[2:3]
	v_cvt_pk_bf16_f32 v148, v148, v149
	s_waitcnt lgkmcnt(1)
	v_add_f32_e32 v144, v144, v152
	s_waitcnt lgkmcnt(0)
	v_add_f32_e32 v145, v145, v153
	v_cndmask_b32_e64 v150, v144, v145, s[4:5]
	ds_bpermute_b32 v150, v175, v150
	v_cndmask_b32_e64 v144, v145, v144, s[4:5]
	v_cvt_pk_bf16_f32 v149, v146, v147
	global_store_dwordx2 v[168:169], v[148:149], off offset:-2048 sc1
	s_waitcnt lgkmcnt(0)
	v_add_f32_e32 v144, v144, v150
	ds_bpermute_b32 v145, v176, v144
	s_waitcnt lgkmcnt(0)
	v_add_f32_e32 v144, v144, v145
	ds_bpermute_b32 v145, v177, v144
	s_waitcnt lgkmcnt(0)
	v_add_f32_e32 v144, v144, v145
	ds_bpermute_b32 v145, v178, v144
	s_and_saveexec_b64 s[24:25], s[6:7]
	s_cbranch_execz .LBB0_45
	s_waitcnt lgkmcnt(0)
	v_add_f32_e32 v144, v144, v145
	v_add_f32_e32 v144, v172, v144
	s_and_saveexec_b64 s[26:27], s[8:9]
	s_cbranch_execz .LBB0_44
; __device__ __forceinline__ void p0_prep(const Params& p, LAS unsigned char* lds) {
;     ...
;             if ((lane & 7) == 0) {
;                 const int j = (h32 ? 4 : 0) + (h16 ? 2 : 0) + (h8 ? 1 : 0);
;                 const float gv = gt + bias_l;
;                 GATES[(size_t)row * 8 + j] = (j < 4) ? gv : (fminf(gv, 0.f) - log1pf(expf(-fabsf(gv))));
	v_mul_f32_e64 v145, |v144|, s28
	v_rndne_f32_e32 v146, v145
	v_sub_f32_e32 v147, v145, v146
	v_fma_f32 v145, |v144|, s28, -v145
	v_fma_f32 v145, |v144|, s29, v145
	v_add_f32_e32 v145, v147, v145
	v_exp_f32_e32 v145, v145
	v_cvt_i32_f32_e32 v146, v146
	v_cmp_ngt_f32_e64 s[0:1], |v144|, s30
	v_max_f32_e32 v147, v144, v144
	v_min_f32_e32 v158, 0, v147
	v_ldexp_f32 v145, v145, v146
	v_cndmask_b32_e64 v145, 0, v145, s[0:1]
	v_cmp_nlt_f32_e64 s[0:1], |v144|, s31
	s_nop 1
	v_cndmask_b32_e64 v159, v180, v145, s[0:1]
	v_add_f32_e32 v146, 1.0, v159
	v_add_f32_e32 v144, -1.0, v146
	v_sub_f32_e32 v145, v144, v146
	v_add_f32_e32 v145, 1.0, v145
	v_sub_f32_e32 v144, v159, v144
	v_add_f32_e32 v147, v144, v145
	v_frexp_mant_f32_e32 v148, v146
	v_cvt_f64_f32_e32 v[144:145], v146
	v_frexp_exp_i32_f64_e32 v144, v[144:145]
	v_cmp_gt_f32_e64 s[0:1], s34, v148
	s_nop 1
	v_subbrev_co_u32_e64 v152, s[0:1], 0, v144, s[0:1]
	v_sub_u32_e32 v144, 0, v152
	v_ldexp_f32 v145, v146, v144
	v_add_f32_e32 v146, -1.0, v145
	v_add_f32_e32 v148, 1.0, v145
	v_ldexp_f32 v144, v147, v144
	v_add_f32_e32 v147, 1.0, v146
	v_add_f32_e32 v149, -1.0, v148
	v_sub_f32_e32 v147, v145, v147
	v_sub_f32_e32 v145, v145, v149
	v_add_f32_e32 v147, v144, v147
	v_add_f32_e32 v144, v144, v145
	v_add_f32_e32 v153, v148, v144
	v_rcp_f32_e32 v155, v153
	v_sub_f32_e32 v145, v148, v153
	v_add_f32_e32 v154, v144, v145
	v_add_f32_e32 v145, v146, v147
	v_mul_f32_e32 v157, v145, v155
	v_sub_f32_e32 v144, v146, v145
	v_mul_f32_e32 v146, v153, v157
	v_fma_f32 v148, v157, v153, -v146
	v_fmac_f32_e32 v148, v157, v154
	v_add_f32_e32 v156, v147, v144
	v_add_f32_e32 v144, v146, v148
	v_sub_f32_e32 v147, v145, v144
	v_pk_add_f32 v[150:151], v[144:145], v[146:147] neg_lo:[0,1] neg_hi:[0,1]
	v_mov_b32_e32 v149, v144
	v_pk_add_f32 v[144:145], v[150:151], v[148:149] neg_lo:[0,1] neg_hi:[0,1]
	v_cmp_neq_f32_e64 s[0:1], s33, v159
	v_add_f32_e32 v145, v156, v145
	v_add_f32_e32 v144, v144, v145
	v_add_f32_e32 v145, v147, v144
	v_mul_f32_e32 v156, v155, v145
	v_mul_f32_e32 v146, v153, v156
	v_fma_f32 v148, v156, v153, -v146
	v_fmac_f32_e32 v148, v156, v154
	v_sub_f32_e32 v147, v147, v145
	v_add_f32_e32 v153, v144, v147
	v_add_f32_e32 v144, v146, v148
	v_sub_f32_e32 v147, v145, v144
	v_pk_add_f32 v[150:151], v[144:145], v[146:147] neg_lo:[0,1] neg_hi:[0,1]
	v_mov_b32_e32 v149, v144
	v_pk_add_f32 v[144:145], v[150:151], v[148:149] neg_lo:[0,1] neg_hi:[0,1]
	s_nop 0
	v_add_f32_e32 v145, v153, v145
	v_add_f32_e32 v144, v144, v145
	v_add_f32_e32 v145, v157, v156
	v_add_f32_e32 v144, v147, v144
	v_sub_f32_e32 v146, v145, v157
	v_mul_f32_e32 v144, v155, v144
	v_sub_f32_e32 v146, v156, v146
	v_add_f32_e32 v146, v146, v144
	v_add_f32_e32 v148, v145, v146
	v_mul_f32_e32 v149, v148, v148
	v_fmamk_f32 v144, v149, 0x3e9b6dac, v179
	v_fmaak_f32 v171, v149, v144, 0x3f2aaada
	v_cvt_f32_i32_e32 v144, v152
	v_sub_f32_e32 v145, v148, v145
	v_sub_f32_e32 v145, v146, v145
	v_ldexp_f32 v150, v145, 1
	v_mul_f32_e32 v145, v148, v149
	v_ldexp_f32 v147, v148, 1
	v_pk_mul_f32 v[148:149], v[144:145], v[170:171]
	s_nop 0
	v_fma_f32 v146, v144, s35, -v148
	v_fmac_f32_e32 v146, 0xb102e308, v144
	v_pk_add_f32 v[144:145], v[148:149], v[146:147]
	s_nop 0
	v_sub_f32_e32 v147, v145, v147
	v_sub_f32_e32 v147, v149, v147
	v_add_f32_e32 v151, v150, v147
	v_mov_b32_e32 v150, v148
	v_pk_add_f32 v[148:149], v[144:145], v[148:149] neg_lo:[0,1] neg_hi:[0,1]
	v_pk_add_f32 v[152:153], v[144:145], v[150:151]
	v_mov_b32_e32 v147, v144
	v_mov_b32_e32 v149, v153
	v_pk_add_f32 v[154:155], v[146:147], v[148:149] neg_lo:[0,1] neg_hi:[0,1]
	v_pk_add_f32 v[146:147], v[146:147], v[148:149]
	v_mov_b32_e32 v150, v151
	v_pk_add_f32 v[148:149], v[146:147], v[144:145] op_sel:[1,0] op_sel_hi:[0,1] neg_lo:[0,1] neg_hi:[0,1]
	v_pk_add_f32 v[156:157], v[152:153], v[148:149] op_sel_hi:[1,0] neg_lo:[0,1] neg_hi:[0,1]
	v_mov_b32_e32 v152, v153
	v_mov_b32_e32 v153, v147
	v_pk_mov_b32 v[148:149], v[144:145], v[148:149] op_sel:[1,0]
	v_mov_b32_e32 v151, v144
	v_pk_add_f32 v[148:149], v[152:153], v[148:149] neg_lo:[0,1] neg_hi:[0,1]
	v_mov_b32_e32 v156, v154
	v_pk_add_f32 v[144:145], v[150:151], v[148:149] neg_lo:[0,1] neg_hi:[0,1]
	v_mov_b32_e32 v155, v147
	v_pk_add_f32 v[148:149], v[156:157], v[144:145]
	s_nop 0
	v_pk_add_f32 v[150:151], v[148:149], v[148:149] op_sel:[0,1] op_sel_hi:[1,0]
	s_nop 0
	v_pk_add_f32 v[146:147], v[146:147], v[150:151] op_sel:[1,0] op_sel_hi:[0,1]
	v_mov_b32_e32 v149, v146
	v_pk_add_f32 v[152:153], v[148:149], v[154:155] neg_lo:[0,1] neg_hi:[0,1]
	v_mov_b32_e32 v145, v150
	v_sub_f32_e32 v147, v148, v152
	v_pk_add_f32 v[144:145], v[144:145], v[152:153] neg_lo:[0,1] neg_hi:[0,1]
	v_sub_f32_e32 v147, v154, v147
	v_add_f32_e32 v144, v144, v147
	v_add_f32_e32 v144, v144, v145
	v_add_f32_e32 v144, v146, v144
	v_cndmask_b32_e64 v144, v180, v144, s[0:1]
	v_cmp_lt_f32_e64 s[0:1], |v159|, s36
	s_nop 1
	v_cndmask_b32_e64 v144, v144, v159, s[0:1]
	v_sub_f32_e32 v144, v158, v144
.LBB0_44:
	s_or_b64 exec, exec, s[26:27]
	global_store_dword v[164:165], v144, off offset:-32 sc1
; #define LAS __attribute__((address_space(3)))
; __device__ __forceinline__ unsigned cvt_pk_bf16(float lo, float hi) { const f32x2_t f = {lo, hi}; const bf16x2_t b = __builtin_convertvector(f, bf16x2_t); return __builtin_bit_cast(unsigned, b); }
; __device__ __forceinline__ void p0_prep(const Params& p, LAS unsigned char* lds) {
;     ...
;         for (int rr = 0; rr < 2; ++rr) {
;             const int row = row0 + rr;
;             float ss = 0.f;
; #pragma unroll
;             for (int i = 0; i < 4; ++i) ss += v[rr][i].x * v[rr][i].x + v[rr][i].y * v[rr][i].y + v[rr][i].z * v[rr][i].z + v[rr][i].w * v[rr][i].w;
;             ss = wave_sum(ss);
;             const float rstd = rsqrtf(ss * (1.0f / 1024.0f) + EPS);
;             float g[8];
; #pragma unroll
;             for (int j = 0; j < 8; ++j) g[j] = 0.f;
; #pragma unroll
;             for (int i = 0; i < 4; ++i) {
;                 const float4 pw = ((const float4*)p.pre_w)[i * 64 + lane];
;                 float hv[4] = {v[rr][i].x * rstd * pw.x, v[rr][i].y * rstd * pw.y, v[rr][i].z * rstd * pw.z, v[rr][i].w * rstd * pw.w};
;                 u32x2 w; w.x = cvt_pk_bf16(hv[0], hv[1]); w.y = cvt_pk_bf16(hv[2], hv[3]);
;                 *(u32x2*)(H + (size_t)row * 1024 + (i * 64 + lane) * 4) = w;
; #pragma unroll
;                 for (int e = 0; e < 4; ++e) {
;                     const int k = (i * 64 + lane) * 4 + e;
;                     const f32x4 wa = *(const LAS f32x4*)(WG + k * 8), wb = *(const LAS f32x4*)(WG + k * 8 + 4);
;                     g[0] += hv[e] * wa[0]; g[1] += hv[e] * wa[1]; g[2] += hv[e] * wa[2]; g[3] += hv[e] * wa[3];
;                     g[4] += hv[e] * wb[0]; g[5] += hv[e] * wb[1]; g[6] += hv[e] * wb[2]; g[7] += hv[e] * wb[3];
;                 }
;             }
.LBB0_45:
	s_or_b64 exec, exec, s[24:25]
	s_waitcnt lgkmcnt(0)
	global_load_dwordx4 v[144:147], v[162:163], off
	v_mov_b32_e32 v150, v141
	v_mov_b32_e32 v151, v137
	v_mov_b32_e32 v148, v140
	v_mov_b32_e32 v149, v136
	v_mov_b32_e32 v158, v133
	v_mov_b32_e32 v159, v129
	v_pk_mul_f32 v[150:151], v[150:151], v[150:151]
	v_mov_b32_e32 v152, v142
	v_mov_b32_e32 v153, v138
	v_mov_b32_e32 v156, v132
	v_mov_b32_e32 v157, v128
	v_pk_mul_f32 v[158:159], v[158:159], v[158:159]
	v_pk_fma_f32 v[148:149], v[148:149], v[148:149], v[150:151]
	v_mov_b32_e32 v154, v143
	v_mov_b32_e32 v155, v139
	v_mov_b32_e32 v182, v134
	v_mov_b32_e32 v183, v130
	v_pk_fma_f32 v[150:151], v[156:157], v[156:157], v[158:159]
	v_pk_fma_f32 v[148:149], v[152:153], v[152:153], v[148:149]
	v_mov_b32_e32 v184, v135
	v_mov_b32_e32 v185, v131
	v_pk_fma_f32 v[150:151], v[182:183], v[182:183], v[150:151]
	v_pk_fma_f32 v[148:149], v[154:155], v[154:155], v[148:149]
	v_pk_fma_f32 v[150:151], v[184:185], v[184:185], v[150:151]
	v_add_f32_e32 v148, v148, v149
	v_add_f32_e32 v148, v148, v150
	v_add_f32_e32 v148, v148, v151
	ds_bpermute_b32 v149, v173, v148
	s_waitcnt lgkmcnt(0)
	v_add_f32_e32 v148, v148, v149
	ds_bpermute_b32 v149, v174, v148
	s_waitcnt lgkmcnt(0)
	v_add_f32_e32 v148, v148, v149
	ds_bpermute_b32 v149, v175, v148
	s_waitcnt lgkmcnt(0)
	v_add_f32_e32 v148, v148, v149
	ds_bpermute_b32 v149, v176, v148
	s_waitcnt lgkmcnt(0)
	v_add_f32_e32 v148, v148, v149
	ds_bpermute_b32 v149, v177, v148
	s_waitcnt lgkmcnt(0)
	v_add_f32_e32 v148, v148, v149
	ds_bpermute_b32 v149, v178, v148
	s_waitcnt lgkmcnt(0)
	v_add_f32_e32 v148, v148, v149
	v_fmamk_f32 v148, v148, 0x3a800000, v161
	v_mul_f32_e32 v149, 0x4b800000, v148
	v_cmp_gt_f32_e64 s[0:1], s13, v148
	s_nop 1
	v_cndmask_b32_e64 v148, v148, v149, s[0:1]
	v_rsq_f32_e32 v148, v148
	s_nop 0
	v_mul_f32_e32 v149, 0x45800000, v148
	v_cndmask_b32_e64 v148, v148, v149, s[0:1]
	v_pk_mul_f32 v[140:141], v[140:141], v[148:149] op_sel_hi:[1,0]
	v_pk_mul_f32 v[142:143], v[142:143], v[148:149] op_sel_hi:[1,0]
	v_pk_mul_f32 v[136:137], v[136:137], v[148:149] op_sel_hi:[1,0]
	v_pk_mul_f32 v[138:139], v[138:139], v[148:149] op_sel_hi:[1,0]
	s_waitcnt vmcnt(0)
	v_pk_mul_f32 v[150:151], v[144:145], v[140:141]
	v_pk_mul_f32 v[140:141], v[146:147], v[142:143]
	v_cvt_pk_bf16_f32 v142, v150, v151
	v_cvt_pk_bf16_f32 v143, v140, v141
	global_store_dwordx2 v[168:169], v[142:143], off offset:-1536 sc1
	global_load_dwordx4 v[142:145], v[162:163], off offset:1024
	v_pk_mul_f32 v[132:133], v[132:133], v[148:149] op_sel_hi:[1,0]
	v_pk_mul_f32 v[134:135], v[134:135], v[148:149] op_sel_hi:[1,0]
	v_pk_mul_f32 v[146:147], v[128:129], v[148:149] op_sel_hi:[1,0]
	v_pk_mul_f32 v[148:149], v[130:131], v[148:149] op_sel_hi:[1,0]
	v_fma_f32 v152, v0, v150, 0
	v_fma_f32 v153, v1, v150, 0
	v_fma_f32 v154, v2, v150, 0
	v_fma_f32 v155, v3, v150, 0
	v_fma_f32 v156, v4, v150, 0
	v_fma_f32 v157, v5, v150, 0
	v_fma_f32 v158, v6, v150, 0
	v_fma_f32 v150, v7, v150, 0
	v_fmac_f32_e32 v152, v8, v151
	v_fmac_f32_e32 v153, v9, v151
	v_fmac_f32_e32 v154, v10, v151
	v_fmac_f32_e32 v155, v11, v151
	v_fmac_f32_e32 v156, v12, v151
	v_fmac_f32_e32 v157, v13, v151
	v_fmac_f32_e32 v158, v14, v151
	v_fmac_f32_e32 v150, v15, v151
	v_fmac_f32_e32 v152, v16, v140
	v_fmac_f32_e32 v153, v17, v140
	v_fmac_f32_e32 v154, v18, v140
	v_fmac_f32_e32 v155, v19, v140
	v_fmac_f32_e32 v156, v20, v140
	v_fmac_f32_e32 v157, v21, v140
	v_fmac_f32_e32 v158, v22, v140
	v_fmac_f32_e32 v150, v23, v140
	v_fmac_f32_e32 v152, v24, v141
	v_fmac_f32_e32 v153, v25, v141
	v_fmac_f32_e32 v154, v26, v141
	v_fmac_f32_e32 v155, v27, v141
	v_fmac_f32_e32 v156, v28, v141
	v_fmac_f32_e32 v157, v29, v141
	v_fmac_f32_e32 v158, v30, v141
	v_fmac_f32_e32 v150, v31, v141
	s_waitcnt vmcnt(0)
	v_pk_mul_f32 v[142:143], v[142:143], v[136:137]
	v_pk_mul_f32 v[144:145], v[144:145], v[138:139]
	v_cvt_pk_bf16_f32 v136, v142, v143
	v_cvt_pk_bf16_f32 v137, v144, v145
	global_store_dwordx2 v[168:169], v[136:137], off offset:-1024 sc1
	global_load_dwordx4 v[136:139], v[162:163], off offset:2048
	v_fmac_f32_e32 v152, v32, v142
	v_fmac_f32_e32 v153, v33, v142
	v_fmac_f32_e32 v154, v34, v142
	v_fmac_f32_e32 v155, v35, v142
	v_fmac_f32_e32 v156, v36, v142
	v_fmac_f32_e32 v157, v37, v142
	v_fmac_f32_e32 v158, v38, v142
	v_fmac_f32_e32 v150, v39, v142
	v_fmac_f32_e32 v152, v40, v143
	v_fmac_f32_e32 v153, v41, v143
	v_fmac_f32_e32 v154, v42, v143
	v_fmac_f32_e32 v155, v43, v143
	v_fmac_f32_e32 v156, v44, v143
	v_fmac_f32_e32 v157, v45, v143
	v_fmac_f32_e32 v158, v46, v143
	v_fmac_f32_e32 v150, v47, v143
	v_fmac_f32_e32 v152, v48, v144
	v_fmac_f32_e32 v153, v49, v144
	v_fmac_f32_e32 v154, v50, v144
	v_fmac_f32_e32 v155, v51, v144
	v_fmac_f32_e32 v156, v52, v144
	v_fmac_f32_e32 v157, v53, v144
	v_fmac_f32_e32 v158, v54, v144
	v_fmac_f32_e32 v150, v55, v144
	v_fmac_f32_e32 v152, v56, v145
	v_fmac_f32_e32 v153, v57, v145
	v_fmac_f32_e32 v154, v58, v145
	v_fmac_f32_e32 v155, v59, v145
	v_fmac_f32_e32 v156, v60, v145
	v_fmac_f32_e32 v157, v61, v145
	v_fmac_f32_e32 v158, v62, v145
	v_fmac_f32_e32 v150, v63, v145
	s_waitcnt vmcnt(0)
; #define LAS __attribute__((address_space(3)))
; __device__ __forceinline__ unsigned cvt_pk_bf16(float lo, float hi) { const f32x2_t f = {lo, hi}; const bf16x2_t b = __builtin_convertvector(f, bf16x2_t); return __builtin_bit_cast(unsigned, b); }
; __device__ __forceinline__ void p0_prep(const Params& p, LAS unsigned char* lds) {
;     ...
;             for (int i = 0; i < 4; ++i) {
;                 const float4 pw = ((const float4*)p.pre_w)[i * 64 + lane];
;                 float hv[4] = {v[rr][i].x * rstd * pw.x, v[rr][i].y * rstd * pw.y, v[rr][i].z * rstd * pw.z, v[rr][i].w * rstd * pw.w};
;                 u32x2 w; w.x = cvt_pk_bf16(hv[0], hv[1]); w.y = cvt_pk_bf16(hv[2], hv[3]);
;                 *(u32x2*)(H + (size_t)row * 1024 + (i * 64 + lane) * 4) = w;
; #pragma unroll
;                 for (int e = 0; e < 4; ++e) {
;                     const int k = (i * 64 + lane) * 4 + e;
;                     const f32x4 wa = *(const LAS f32x4*)(WG + k * 8), wb = *(const LAS f32x4*)(WG + k * 8 + 4);
;                     g[0] += hv[e] * wa[0]; g[1] += hv[e] * wa[1]; g[2] += hv[e] * wa[2]; g[3] += hv[e] * wa[3];
;                     g[4] += hv[e] * wb[0]; g[5] += hv[e] * wb[1]; g[6] += hv[e] * wb[2]; g[7] += hv[e] * wb[3];
;                 }
;             }
;             const bool h32 = (lane & 32) != 0, h16 = (lane & 16) != 0, h8 = (lane & 8) != 0;
;             float t4[4], t2[2];
; #pragma unroll
;             for (int j = 0; j < 4; ++j) { const float send = h32 ? g[j] : g[j + 4], keep = h32 ? g[j + 4] : g[j]; t4[j] = keep + __shfl_xor(send, 32); }
; #pragma unroll
;             for (int j = 0; j < 2; ++j) { const float send = h16 ? t4[j] : t4[j + 2], keep = h16 ? t4[j + 2] : t4[j]; t2[j] = keep + __shfl_xor(send, 16); }
;             float gt; { const float send = h8 ? t2[0] : t2[1], keep = h8 ? t2[1] : t2[0]; gt = keep + __shfl_xor(send, 8); }
;             gt += __shfl_xor(gt, 4); gt += __shfl_xor(gt, 2); gt += __shfl_xor(gt, 1);
;             if ((lane & 7) == 0) {
	v_pk_mul_f32 v[132:133], v[132:133], v[136:137]
	v_pk_mul_f32 v[134:135], v[134:135], v[138:139]
	v_cvt_pk_bf16_f32 v128, v132, v133
	v_cvt_pk_bf16_f32 v129, v134, v135
	global_store_dwordx2 v[168:169], v[128:129], off offset:-512 sc1
	global_load_dwordx4 v[128:131], v[162:163], off offset:3072
	v_fmac_f32_e32 v152, v64, v132
	v_fmac_f32_e32 v153, v65, v132
	v_fmac_f32_e32 v154, v66, v132
	v_fmac_f32_e32 v155, v67, v132
	v_fmac_f32_e32 v156, v68, v132
	v_fmac_f32_e32 v157, v69, v132
	v_fmac_f32_e32 v158, v70, v132
	v_fmac_f32_e32 v150, v71, v132
	v_fmac_f32_e32 v152, v72, v133
	v_fmac_f32_e32 v153, v73, v133
	v_fmac_f32_e32 v154, v74, v133
	v_fmac_f32_e32 v155, v75, v133
	v_fmac_f32_e32 v156, v76, v133
	v_fmac_f32_e32 v157, v77, v133
	v_fmac_f32_e32 v158, v78, v133
	v_fmac_f32_e32 v150, v79, v133
	v_fmac_f32_e32 v152, v80, v134
	v_fmac_f32_e32 v153, v81, v134
	v_fmac_f32_e32 v154, v82, v134
	v_fmac_f32_e32 v155, v83, v134
	v_fmac_f32_e32 v156, v84, v134
	v_fmac_f32_e32 v157, v85, v134
	v_fmac_f32_e32 v158, v86, v134
	v_fmac_f32_e32 v150, v87, v134
	v_fmac_f32_e32 v152, v88, v135
	v_fmac_f32_e32 v153, v89, v135
	v_fmac_f32_e32 v154, v90, v135
	v_fmac_f32_e32 v155, v91, v135
	v_fmac_f32_e32 v156, v92, v135
	v_fmac_f32_e32 v157, v93, v135
	v_fmac_f32_e32 v158, v94, v135
	v_fmac_f32_e32 v150, v95, v135
	s_waitcnt vmcnt(0)
	v_pk_mul_f32 v[132:133], v[146:147], v[128:129]
	s_nop 0
	v_fmac_f32_e32 v152, v96, v132
	v_fmac_f32_e32 v153, v97, v132
	v_fmac_f32_e32 v154, v98, v132
	v_fmac_f32_e32 v155, v99, v132
	v_fmac_f32_e32 v156, v100, v132
	v_fmac_f32_e32 v157, v101, v132
	v_fmac_f32_e32 v158, v102, v132
	v_fmac_f32_e32 v150, v103, v132
	v_pk_mul_f32 v[130:131], v[148:149], v[130:131]
	v_fmac_f32_e32 v152, v104, v133
	v_fmac_f32_e32 v153, v105, v133
	v_fmac_f32_e32 v154, v106, v133
	v_fmac_f32_e32 v155, v107, v133
	v_fmac_f32_e32 v156, v108, v133
	v_fmac_f32_e32 v157, v109, v133
	v_fmac_f32_e32 v158, v110, v133
	v_fmac_f32_e32 v150, v111, v133
	v_fmac_f32_e32 v152, v112, v130
	v_fmac_f32_e32 v153, v113, v130
	v_fmac_f32_e32 v154, v114, v130
	v_fmac_f32_e32 v155, v115, v130
	v_fmac_f32_e32 v156, v116, v130
	v_fmac_f32_e32 v157, v117, v130
	v_fmac_f32_e32 v158, v118, v130
	v_fmac_f32_e32 v150, v119, v130
	v_fmac_f32_e32 v152, v120, v131
	v_fmac_f32_e32 v153, v121, v131
	v_fmac_f32_e32 v154, v122, v131
	v_fmac_f32_e32 v155, v123, v131
	v_fmac_f32_e32 v156, v124, v131
	v_fmac_f32_e32 v157, v125, v131
	v_fmac_f32_e32 v158, v126, v131
	v_fmac_f32_e32 v150, v127, v131
	v_cndmask_b32_e32 v128, v152, v156, vcc
	v_cndmask_b32_e32 v134, v153, v157, vcc
	v_cndmask_b32_e32 v136, v154, v158, vcc
	v_cndmask_b32_e32 v138, v155, v150, vcc
	ds_bpermute_b32 v128, v173, v128
	ds_bpermute_b32 v134, v173, v134
	ds_bpermute_b32 v136, v173, v136
	ds_bpermute_b32 v138, v173, v138
	v_cndmask_b32_e32 v129, v156, v152, vcc
	v_cndmask_b32_e32 v135, v157, v153, vcc
	v_cndmask_b32_e32 v137, v158, v154, vcc
	v_cndmask_b32_e32 v139, v150, v155, vcc
	s_waitcnt lgkmcnt(3)
	v_add_f32_e32 v128, v129, v128
	s_waitcnt lgkmcnt(2)
	v_add_f32_e32 v129, v135, v134
	s_waitcnt lgkmcnt(1)
	v_add_f32_e32 v134, v137, v136
	s_waitcnt lgkmcnt(0)
	v_add_f32_e32 v135, v139, v138
	v_cndmask_b32_e64 v136, v128, v134, s[2:3]
	v_cndmask_b32_e64 v137, v129, v135, s[2:3]
	ds_bpermute_b32 v136, v174, v136
	ds_bpermute_b32 v137, v174, v137
	v_cndmask_b32_e64 v128, v134, v128, s[2:3]
	v_cndmask_b32_e64 v129, v135, v129, s[2:3]
	v_cvt_pk_bf16_f32 v132, v132, v133
	s_waitcnt lgkmcnt(1)
	v_add_f32_e32 v128, v128, v136
	s_waitcnt lgkmcnt(0)
	v_add_f32_e32 v129, v129, v137
	v_cndmask_b32_e64 v134, v128, v129, s[4:5]
	ds_bpermute_b32 v134, v175, v134
	v_cndmask_b32_e64 v128, v129, v128, s[4:5]
	v_cvt_pk_bf16_f32 v133, v130, v131
	global_store_dwordx2 v[168:169], v[132:133], off sc1
	s_waitcnt lgkmcnt(0)
	v_add_f32_e32 v128, v128, v134
	ds_bpermute_b32 v129, v176, v128
	s_waitcnt lgkmcnt(0)
	v_add_f32_e32 v128, v128, v129
	ds_bpermute_b32 v129, v177, v128
	s_waitcnt lgkmcnt(0)
	v_add_f32_e32 v128, v128, v129
	ds_bpermute_b32 v129, v178, v128
	s_and_saveexec_b64 s[24:25], s[6:7]
	s_cbranch_execz .LBB0_40
	s_waitcnt lgkmcnt(0)
	v_add_f32_e32 v128, v128, v129
	v_add_f32_e32 v128, v172, v128
	s_and_saveexec_b64 s[26:27], s[8:9]
	s_cbranch_execz .LBB0_39
; __device__ __forceinline__ void p0_prep(const Params& p, LAS unsigned char* lds) {
;     ...
;             if ((lane & 7) == 0) {
;                 const int j = (h32 ? 4 : 0) + (h16 ? 2 : 0) + (h8 ? 1 : 0);
;                 const float gv = gt + bias_l;
;                 GATES[(size_t)row * 8 + j] = (j < 4) ? gv : (fminf(gv, 0.f) - log1pf(expf(-fabsf(gv))));
;             }
	v_mul_f32_e64 v129, |v128|, s28
	v_rndne_f32_e32 v130, v129
	v_sub_f32_e32 v131, v129, v130
	v_fma_f32 v129, |v128|, s28, -v129
	v_fma_f32 v129, |v128|, s29, v129
	v_add_f32_e32 v129, v131, v129
	v_exp_f32_e32 v129, v129
	v_cvt_i32_f32_e32 v130, v130
	v_cmp_ngt_f32_e64 s[0:1], |v128|, s30
	v_max_f32_e32 v131, v128, v128
	v_min_f32_e32 v142, 0, v131
	v_ldexp_f32 v129, v129, v130
	v_cndmask_b32_e64 v129, 0, v129, s[0:1]
	v_cmp_nlt_f32_e64 s[0:1], |v128|, s31
	s_nop 1
	v_cndmask_b32_e64 v143, v180, v129, s[0:1]
	v_add_f32_e32 v130, 1.0, v143
	v_add_f32_e32 v128, -1.0, v130
	v_sub_f32_e32 v129, v128, v130
	v_add_f32_e32 v129, 1.0, v129
	v_sub_f32_e32 v128, v143, v128
	v_add_f32_e32 v131, v128, v129
	v_frexp_mant_f32_e32 v132, v130
	v_cvt_f64_f32_e32 v[128:129], v130
	v_frexp_exp_i32_f64_e32 v128, v[128:129]
	v_cmp_gt_f32_e64 s[0:1], s34, v132
	s_nop 1
	v_subbrev_co_u32_e64 v136, s[0:1], 0, v128, s[0:1]
	v_sub_u32_e32 v128, 0, v136
	v_ldexp_f32 v129, v130, v128
	v_add_f32_e32 v130, -1.0, v129
	v_add_f32_e32 v132, 1.0, v129
	v_ldexp_f32 v128, v131, v128
	v_add_f32_e32 v131, 1.0, v130
	v_add_f32_e32 v133, -1.0, v132
	v_sub_f32_e32 v131, v129, v131
	v_sub_f32_e32 v129, v129, v133
	v_add_f32_e32 v131, v128, v131
	v_add_f32_e32 v128, v128, v129
	v_add_f32_e32 v137, v132, v128
	v_rcp_f32_e32 v139, v137
	v_sub_f32_e32 v129, v132, v137
	v_add_f32_e32 v138, v128, v129
	v_add_f32_e32 v129, v130, v131
	v_mul_f32_e32 v141, v129, v139
	v_sub_f32_e32 v128, v130, v129
	v_mul_f32_e32 v130, v137, v141
	v_fma_f32 v132, v141, v137, -v130
	v_fmac_f32_e32 v132, v141, v138
	v_add_f32_e32 v140, v131, v128
	v_add_f32_e32 v128, v130, v132
	v_sub_f32_e32 v131, v129, v128
	v_pk_add_f32 v[134:135], v[128:129], v[130:131] neg_lo:[0,1] neg_hi:[0,1]
	v_mov_b32_e32 v133, v128
	v_pk_add_f32 v[128:129], v[134:135], v[132:133] neg_lo:[0,1] neg_hi:[0,1]
	v_cmp_neq_f32_e64 s[0:1], s33, v143
	v_add_f32_e32 v129, v140, v129
	v_add_f32_e32 v128, v128, v129
	v_add_f32_e32 v129, v131, v128
	v_mul_f32_e32 v140, v139, v129
	v_mul_f32_e32 v130, v137, v140
	v_fma_f32 v132, v140, v137, -v130
	v_fmac_f32_e32 v132, v140, v138
	v_sub_f32_e32 v131, v131, v129
	v_add_f32_e32 v137, v128, v131
	v_add_f32_e32 v128, v130, v132
	v_sub_f32_e32 v131, v129, v128
	v_pk_add_f32 v[134:135], v[128:129], v[130:131] neg_lo:[0,1] neg_hi:[0,1]
	v_mov_b32_e32 v133, v128
	v_pk_add_f32 v[128:129], v[134:135], v[132:133] neg_lo:[0,1] neg_hi:[0,1]
	s_nop 0
	v_add_f32_e32 v129, v137, v129
	v_add_f32_e32 v128, v128, v129
	v_add_f32_e32 v129, v141, v140
	v_add_f32_e32 v128, v131, v128
	v_sub_f32_e32 v130, v129, v141
	v_mul_f32_e32 v128, v139, v128
	v_sub_f32_e32 v130, v140, v130
	v_add_f32_e32 v130, v130, v128
	v_add_f32_e32 v132, v129, v130
	v_mul_f32_e32 v133, v132, v132
	v_fmamk_f32 v128, v133, 0x3e9b6dac, v179
	v_fmaak_f32 v171, v133, v128, 0x3f2aaada
	v_cvt_f32_i32_e32 v128, v136
	v_sub_f32_e32 v129, v132, v129
	v_sub_f32_e32 v129, v130, v129
	v_ldexp_f32 v134, v129, 1
	v_mul_f32_e32 v129, v132, v133
	v_ldexp_f32 v131, v132, 1
	v_pk_mul_f32 v[132:133], v[128:129], v[170:171]
	s_nop 0
	v_fma_f32 v130, v128, s35, -v132
	v_fmac_f32_e32 v130, 0xb102e308, v128
	v_pk_add_f32 v[128:129], v[132:133], v[130:131]
	s_nop 0
	v_sub_f32_e32 v131, v129, v131
	v_sub_f32_e32 v131, v133, v131
	v_add_f32_e32 v135, v134, v131
	v_mov_b32_e32 v134, v132
	v_pk_add_f32 v[132:133], v[128:129], v[132:133] neg_lo:[0,1] neg_hi:[0,1]
	v_pk_add_f32 v[136:137], v[128:129], v[134:135]
	v_mov_b32_e32 v131, v128
	v_mov_b32_e32 v133, v137
	v_pk_add_f32 v[138:139], v[130:131], v[132:133] neg_lo:[0,1] neg_hi:[0,1]
	v_pk_add_f32 v[130:131], v[130:131], v[132:133]
	v_mov_b32_e32 v134, v135
	v_pk_add_f32 v[132:133], v[130:131], v[128:129] op_sel:[1,0] op_sel_hi:[0,1] neg_lo:[0,1] neg_hi:[0,1]
	v_pk_add_f32 v[140:141], v[136:137], v[132:133] op_sel_hi:[1,0] neg_lo:[0,1] neg_hi:[0,1]
	v_mov_b32_e32 v136, v137
	v_mov_b32_e32 v137, v131
	v_pk_mov_b32 v[132:133], v[128:129], v[132:133] op_sel:[1,0]
	v_mov_b32_e32 v135, v128
	v_pk_add_f32 v[132:133], v[136:137], v[132:133] neg_lo:[0,1] neg_hi:[0,1]
	v_mov_b32_e32 v140, v138
	v_pk_add_f32 v[128:129], v[134:135], v[132:133] neg_lo:[0,1] neg_hi:[0,1]
	v_mov_b32_e32 v139, v131
	v_pk_add_f32 v[132:133], v[140:141], v[128:129]
	s_nop 0
	v_pk_add_f32 v[134:135], v[132:133], v[132:133] op_sel:[0,1] op_sel_hi:[1,0]
	s_nop 0
	v_pk_add_f32 v[130:131], v[130:131], v[134:135] op_sel:[1,0] op_sel_hi:[0,1]
	v_mov_b32_e32 v133, v130
	v_pk_add_f32 v[136:137], v[132:133], v[138:139] neg_lo:[0,1] neg_hi:[0,1]
	v_mov_b32_e32 v129, v134
	v_sub_f32_e32 v131, v132, v136
	v_pk_add_f32 v[128:129], v[128:129], v[136:137] neg_lo:[0,1] neg_hi:[0,1]
	v_sub_f32_e32 v131, v138, v131
	v_add_f32_e32 v128, v128, v131
	v_add_f32_e32 v128, v128, v129
	v_add_f32_e32 v128, v130, v128
	v_cndmask_b32_e64 v128, v180, v128, s[0:1]
	v_cmp_lt_f32_e64 s[0:1], |v143|, s36
	s_nop 1
	v_cndmask_b32_e64 v128, v128, v143, s[0:1]
	v_sub_f32_e32 v128, v142, v128
	s_branch .LBB0_39

; __device__ __forceinline__ void p0_prep(const Params& p, LAS unsigned char* lds) {
;     ...
;     float* RC = (float*)(ws + WS_ROPE); float* RS = RC + 2048 * 16;
;     for (int idx = bid * 512 + tid; idx < 2048 * 16; idx += G * 512) {
;         const int pos = idx >> 4, i = idx & 15;
;         const float inv = powf(500000.0f, -(float)(2 * i) / 32.0f);
;         const float ang = (float)pos * inv;
;         RC[idx] = cosf(ang); RS[idx] = sinf(ang);
;     }
.LBB0_50:
	s_or_b64 exec, exec, s[0:1]
	v_mul_f32_e32 v4, v20, v20
	v_fmamk_f32 v17, v4, 0xb94c1982, v10
	v_fmaak_f32 v17, v4, v17, 0xbe2aaa9d
	v_mul_f32_e32 v17, v4, v17
	v_fmac_f32_e32 v20, v20, v17
	v_fmamk_f32 v17, v4, 0x37d75334, v11
	v_fmaak_f32 v17, v4, v17, 0x3d2aabf7
	v_fmaak_f32 v17, v4, v17, 0xbf000004
	v_fma_f32 v4, v4, v17, 1.0
	v_and_b32_e32 v17, 1, v19
	v_cmp_eq_u32_e64 s[0:1], 0, v17
	v_lshlrev_b32_e32 v17, 30, v19
	v_and_b32_e32 v17, 0x80000000, v17
	v_xor_b32_e32 v15, v16, v15
	v_cndmask_b32_e64 v4, v4, v20, s[0:1]
	v_xor_b32_e32 v15, v15, v17
	v_xor_b32_e32 v4, v15, v4
	v_cndmask_b32_e32 v4, v14, v4, vcc
	v_add_co_u32_e32 v16, vcc, 0x20000, v2
	v_add_u32_e32 v0, s12, v0
	s_nop 0
	v_addc_co_u32_e32 v17, vcc, 0, v3, vcc
	v_cmp_lt_i32_e32 vcc, s41, v0
	v_lshl_add_u64 v[2:3], v[2:3], 0, s[14:15]
	s_or_b64 s[16:17], vcc, s[16:17]
	v_add_u32_e32 v1, s13, v1
	global_store_dword v[16:17], v4, off sc1
	s_andn2_b64 exec, exec, s[16:17]
	s_cbranch_execz .LBB0_59

; __device__ __forceinline__ void p0_prep(const Params& p, LAS unsigned char* lds) {
;     ...
;     float* RC = (float*)(ws + WS_ROPE); float* RS = RC + 2048 * 16;
;     for (int idx = bid * 512 + tid; idx < 2048 * 16; idx += G * 512) {
;         const int pos = idx >> 4, i = idx & 15;
;         const float inv = powf(500000.0f, -(float)(2 * i) / 32.0f);
;         const float ang = (float)pos * inv;
;         RC[idx] = cosf(ang); RS[idx] = sinf(ang);
;     }
.LBB0_53:
	s_or_saveexec_b64 s[0:1], s[18:19]
	v_mul_f32_e64 v4, |v15|, s37
	v_rndne_f32_e32 v4, v4
	s_xor_b64 exec, exec, s[0:1]
	v_cvt_i32_f32_e32 v19, v4
	v_fma_f32 v20, v4, s38, |v15|
	v_fmac_f32_e32 v20, 0xb3a22168, v4
	v_fmac_f32_e32 v20, 0xa7c234c4, v4
	s_or_b64 exec, exec, s[0:1]
	v_mul_f32_e32 v21, v20, v20
	v_fmamk_f32 v22, v21, 0xb94c1982, v10
	v_fmaak_f32 v22, v21, v22, 0xbe2aaa9d
	v_mul_f32_e32 v22, v21, v22
	v_fmac_f32_e32 v20, v20, v22
	v_fmamk_f32 v22, v21, 0x37d75334, v11
	v_fmaak_f32 v22, v21, v22, 0x3d2aabf7
	v_fmaak_f32 v22, v21, v22, 0xbf000004
	v_fma_f32 v21, v21, v22, 1.0
	v_and_b32_e32 v22, 1, v19
	v_cmp_eq_u32_e32 vcc, 0, v22
	v_lshlrev_b32_e32 v19, 30, v19
	s_nop 0
	v_cndmask_b32_e64 v20, -v20, v21, vcc
	v_bitop3_b32 v19, v19, v20, s39 bitop3:0x6c
	v_cmp_class_f32_e64 vcc, v15, s40
	s_nop 1
	v_cndmask_b32_e32 v19, v14, v19, vcc
	global_store_dword v[2:3], v19, off sc1
	s_and_saveexec_b64 s[0:1], s[6:7]
	s_xor_b64 s[18:19], exec, s[0:1]
	s_cbranch_execz .LBB0_57
	v_cmp_lt_u32_e64 s[0:1], 63, v18
	s_nop 1
	v_cndmask_b32_e64 v4, 0, v12, s[0:1]
	v_add_u32_e32 v4, v4, v18
	v_cmp_lt_u32_e64 s[2:3], 31, v4
	s_nop 1
	v_cndmask_b32_e64 v18, 0, v13, s[2:3]
	v_add_u32_e32 v4, v18, v4
	v_cmp_lt_u32_e64 s[4:5], 31, v4
	s_nop 1
	v_cndmask_b32_e64 v18, 0, v13, s[4:5]
	v_add_u32_e32 v32, v18, v4
	v_mad_u64_u32 v[18:19], s[6:7], v17, s28, 0
	v_mov_b32_e32 v4, v19
	v_mad_u64_u32 v[20:21], s[6:7], v17, s29, v[4:5]
	v_mov_b32_e32 v4, v21
	v_mad_u64_u32 v[22:23], s[6:7], v17, s30, v[4:5]
	v_mov_b32_e32 v4, v23
	v_mad_u64_u32 v[24:25], s[6:7], v17, s31, v[4:5]
	v_mov_b32_e32 v4, v25
	v_mad_u64_u32 v[26:27], s[6:7], v17, s33, v[4:5]
	v_mov_b32_e32 v4, v27
	v_mad_u64_u32 v[28:29], s[6:7], v17, s34, v[4:5]
	v_mov_b32_e32 v4, v29
	v_mad_u64_u32 v[30:31], s[6:7], v17, s35, v[4:5]
	v_cndmask_b32_e64 v19, v28, v24, s[0:1]
	v_cndmask_b32_e64 v4, v30, v26, s[0:1]
	v_cndmask_b32_e64 v21, v31, v28, s[0:1]
	v_cndmask_b32_e64 v17, v4, v19, s[2:3]
	v_cndmask_b32_e64 v4, v21, v4, s[2:3]
	v_cndmask_b32_e64 v21, v26, v22, s[0:1]
	v_cndmask_b32_e64 v19, v19, v21, s[2:3]
	v_cndmask_b32_e64 v20, v24, v20, s[0:1]
	v_cndmask_b32_e64 v4, v4, v17, s[4:5]
	v_cndmask_b32_e64 v17, v17, v19, s[4:5]
	v_sub_u32_e32 v23, 32, v32
	v_cndmask_b32_e64 v21, v21, v20, s[2:3]
	v_alignbit_b32 v25, v4, v17, v23
	v_cmp_eq_u32_e64 s[6:7], 0, v32
	v_cndmask_b32_e64 v19, v19, v21, s[4:5]
	v_alignbit_b32 v24, v17, v19, v23
	v_cndmask_b32_e64 v4, v25, v4, s[6:7]
	v_cndmask_b32_e64 v18, v22, v18, s[0:1]
	v_cndmask_b32_e64 v17, v24, v17, s[6:7]
	v_bfe_u32 v26, v4, 29, 1
	v_cndmask_b32_e64 v18, v20, v18, s[2:3]
	v_alignbit_b32 v24, v4, v17, 30
	v_sub_u32_e32 v27, 0, v26
	v_cndmask_b32_e64 v18, v21, v18, s[4:5]
	v_xor_b32_e32 v24, v24, v27
	v_alignbit_b32 v20, v19, v18, v23
	v_cndmask_b32_e64 v19, v20, v19, s[6:7]
	v_ffbh_u32_e32 v20, v24
	v_alignbit_b32 v17, v17, v19, 30
	v_min_u32_e32 v20, 32, v20
	v_alignbit_b32 v18, v19, v18, 30
	v_xor_b32_e32 v17, v17, v27
	v_sub_u32_e32 v21, 31, v20
	v_xor_b32_e32 v18, v18, v27
	v_alignbit_b32 v22, v24, v17, v21
	v_alignbit_b32 v17, v17, v18, v21
	v_alignbit_b32 v18, v22, v17, 9
	v_ffbh_u32_e32 v19, v18
	v_min_u32_e32 v19, 32, v19
	v_lshrrev_b32_e32 v25, 29, v4
	v_not_b32_e32 v21, v19
	v_alignbit_b32 v17, v18, v17, v21
	v_lshlrev_b32_e32 v18, 31, v25
	v_or_b32_e32 v21, 0x33000000, v18
	v_add_lshl_u32 v19, v19, v20, 23
	v_lshrrev_b32_e32 v17, 9, v17
	v_sub_u32_e32 v19, v21, v19
	v_or_b32_e32 v18, 0.5, v18
	v_lshlrev_b32_e32 v20, 23, v20
	v_or_b32_e32 v17, v19, v17
	v_lshrrev_b32_e32 v19, 9, v22
	v_sub_u32_e32 v18, v18, v20
	v_or_b32_e32 v18, v19, v18
	v_mul_f32_e32 v19, 0x3fc90fda, v18
	v_fma_f32 v20, v18, s36, -v19
	v_fmac_f32_e32 v20, 0x33a22168, v18
	v_fmac_f32_e32 v20, 0x3fc90fda, v17
	v_lshrrev_b32_e32 v4, 30, v4
	v_add_f32_e32 v20, v19, v20
	v_add_u32_e32 v19, v26, v4
